# S4 Hyena transpose: Z loads remapped so each instruction reads one contiguous 64 B per channel row (16 lines/instr instead of 32), LDS write conflicts 4-way -> 2-way
# speedup vs baseline: 1.0063x; 1.0014x over previous
; DI u32 pack2(float a, float b) { return (u32)f2bf(a) | ((u32)f2bf(b) << 16); }
; DI float bflo(u32 v) { return __uint_as_float(v << 16); }
; DI float bfhi(u32 v) { return __uint_as_float(v & 0xffff0000u); }
; DI float silu_f(float x) { return x / (1.f + __expf(-x)); }
; DI void phase_ssd_combine(const Params& p, int l, int bid, int nblk) {
;     ...
;   for (int row = bid * 4 + w; row < ROWS; row += nblk * 4) {
;     const int pos = row % TPB;
;     if (l == 1 && pos < CTXL) continue;
;     const uint4 vf = *(const uint4*)(YF + (size_t)row * 512 + c0);
;     const uint4 vb = *(const uint4*)(YB + (size_t)row * 512 + c0);
;     const uint4 vx = *(const uint4*)(XBCA + (size_t)row * 1024 + c0);
;     const uint4 vz = *(const uint4*)(PZ + (size_t)row * 512 + c0);
;     const u32 af_[4] = {vf.x, vf.y, vf.z, vf.w}, ab_[4] = {vb.x, vb.y, vb.z, vb.w};
;     const u32 ax_[4] = {vx.x, vx.y, vx.z, vx.w}, az_[4] = {vz.x, vz.y, vz.z, vz.w};
;     float y[8];
;     float ss = 0.f;
; #pragma unroll
;     for (int i = 0; i < 4; ++i) {
;       const float y0 = bflo(af_[i]) + bflo(ab_[i]) + dsk * bflo(ax_[i]);
;       const float y1 = bfhi(af_[i]) + bfhi(ab_[i]) + dsk * bfhi(ax_[i]);
;       y[2 * i] = y0 * silu_f(bflo(az_[i]));
;       y[2 * i + 1] = y1 * silu_f(bfhi(az_[i]));
;       ss += y[2 * i] * y[2 * i] + y[2 * i + 1] * y[2 * i + 1];
;     }
; #pragma unroll
;     for (int o = 16; o >= 1; o >>= 1) ss += __shfl_xor(ss, o);
;     const float rs = rsqrtf(ss * (1.f / 256.f) + EPSF);
;     float o8[8];
; #pragma unroll
;     for (int i = 0; i < 8; ++i) o8[i] = y[i] * rs * ng[c0 + i];
;     uint4 o = {pack2(o8[0], o8[1]), pack2(o8[2], o8[3]), pack2(o8[4], o8[5]), pack2(o8[6], o8[7])};
;     *(uint4*)&YM[(size_t)row * 1024 + 256 + c0] = o;
.Lcmb_top:
	s_waitcnt vmcnt(5)
	v_lshlrev_b32_e32 v64, 16, v32
	v_and_b32_e32 v65, 0xffff0000, v32
	v_lshlrev_b32_e32 v66, 16, v33
	v_and_b32_e32 v67, 0xffff0000, v33
	v_lshlrev_b32_e32 v68, 16, v34
	v_and_b32_e32 v69, 0xffff0000, v34
	v_lshlrev_b32_e32 v70, 16, v35
	v_and_b32_e32 v71, 0xffff0000, v35
	v_lshlrev_b32_e32 v80, 16, v36
	v_and_b32_e32 v81, 0xffff0000, v36
	v_lshlrev_b32_e32 v82, 16, v37
	v_and_b32_e32 v83, 0xffff0000, v37
	v_lshlrev_b32_e32 v84, 16, v38
	v_and_b32_e32 v85, 0xffff0000, v38
	v_lshlrev_b32_e32 v86, 16, v39
	v_and_b32_e32 v87, 0xffff0000, v39
	v_add_f32_e32 v64, v64, v80
	v_add_f32_e32 v65, v65, v81
	v_add_f32_e32 v66, v66, v82
	v_add_f32_e32 v67, v67, v83
	v_add_f32_e32 v68, v68, v84
	v_add_f32_e32 v69, v69, v85
	v_add_f32_e32 v70, v70, v86
	v_add_f32_e32 v71, v71, v87
	v_lshlrev_b32_e32 v80, 16, v40
	v_and_b32_e32 v81, 0xffff0000, v40
	v_lshlrev_b32_e32 v82, 16, v41
	v_and_b32_e32 v83, 0xffff0000, v41
	v_lshlrev_b32_e32 v84, 16, v42
	v_and_b32_e32 v85, 0xffff0000, v42
	v_lshlrev_b32_e32 v86, 16, v43
	v_and_b32_e32 v87, 0xffff0000, v43
	v_fmac_f32_e32 v64, v24, v80
	v_fmac_f32_e32 v65, v24, v81
	v_fmac_f32_e32 v66, v24, v82
	v_fmac_f32_e32 v67, v24, v83
	v_fmac_f32_e32 v68, v24, v84
	v_fmac_f32_e32 v69, v24, v85
	v_fmac_f32_e32 v70, v24, v86
	v_fmac_f32_e32 v71, v24, v87
	v_lshlrev_b32_e32 v72, 16, v44
	v_and_b32_e32 v73, 0xffff0000, v44
	v_lshlrev_b32_e32 v74, 16, v45
	v_and_b32_e32 v75, 0xffff0000, v45
	v_lshlrev_b32_e32 v76, 16, v46
	v_and_b32_e32 v77, 0xffff0000, v46
	v_lshlrev_b32_e32 v78, 16, v47
	v_and_b32_e32 v79, 0xffff0000, v47
	v_mul_f32_e32 v80, 0xbfb8aa3b, v72
	v_mul_f32_e32 v81, 0xbfb8aa3b, v73
	v_mul_f32_e32 v82, 0xbfb8aa3b, v74
	v_mul_f32_e32 v83, 0xbfb8aa3b, v75
	v_mul_f32_e32 v84, 0xbfb8aa3b, v76
	v_mul_f32_e32 v85, 0xbfb8aa3b, v77
	v_mul_f32_e32 v86, 0xbfb8aa3b, v78
	v_mul_f32_e32 v87, 0xbfb8aa3b, v79
	v_exp_f32_e32 v80, v80
	v_exp_f32_e32 v81, v81
	v_exp_f32_e32 v82, v82
	v_exp_f32_e32 v83, v83
	v_exp_f32_e32 v84, v84
	v_exp_f32_e32 v85, v85
	v_exp_f32_e32 v86, v86
	v_exp_f32_e32 v87, v87
	v_add_f32_e32 v80, 1.0, v80
	v_add_f32_e32 v81, 1.0, v81
	v_add_f32_e32 v82, 1.0, v82
	v_add_f32_e32 v83, 1.0, v83
	v_add_f32_e32 v84, 1.0, v84
	v_add_f32_e32 v85, 1.0, v85
	v_add_f32_e32 v86, 1.0, v86
	v_add_f32_e32 v87, 1.0, v87
	v_rcp_f32_e32 v80, v80
	v_rcp_f32_e32 v81, v81
	v_rcp_f32_e32 v82, v82
	v_rcp_f32_e32 v83, v83
	v_rcp_f32_e32 v84, v84
	v_rcp_f32_e32 v85, v85
	v_rcp_f32_e32 v86, v86
	v_rcp_f32_e32 v87, v87
	v_mul_f32_e32 v72, v72, v80
	v_mul_f32_e32 v73, v73, v81
	v_mul_f32_e32 v74, v74, v82
	v_mul_f32_e32 v75, v75, v83
	v_mul_f32_e32 v76, v76, v84
	v_mul_f32_e32 v77, v77, v85
	v_mul_f32_e32 v78, v78, v86
	v_mul_f32_e32 v79, v79, v87
	v_mul_f32_e32 v64, v64, v72
	v_mul_f32_e32 v65, v65, v73
	v_mul_f32_e32 v66, v66, v74
	v_mul_f32_e32 v67, v67, v75
	v_mul_f32_e32 v68, v68, v76
	v_mul_f32_e32 v69, v69, v77
	v_mul_f32_e32 v70, v70, v78
	v_mul_f32_e32 v71, v71, v79
	v_mul_f32_e32 v7, v64, v64
	v_fmac_f32_e32 v7, v65, v65
	v_fmac_f32_e32 v7, v66, v66
	v_fmac_f32_e32 v7, v67, v67
	v_fmac_f32_e32 v7, v68, v68
	v_fmac_f32_e32 v7, v69, v69
	v_fmac_f32_e32 v7, v70, v70
	v_fmac_f32_e32 v7, v71, v71
	s_nop 1
	v_add_f32_dpp v7, v7, v7 quad_perm:[1,0,3,2] row_mask:0xf bank_mask:0xf
	s_nop 1
	v_add_f32_dpp v7, v7, v7 quad_perm:[2,3,0,1] row_mask:0xf bank_mask:0xf
	s_nop 1
	v_add_f32_dpp v7, v7, v7 row_half_mirror row_mask:0xf bank_mask:0xf
	s_nop 1
	v_add_f32_dpp v7, v7, v7 row_mirror row_mask:0xf bank_mask:0xf
	s_nop 1
	ds_bpermute_b32 v8, v5, v7
	s_waitcnt lgkmcnt(0)
	v_add_f32_e32 v7, v7, v8
	v_mov_b32_e32 v8, 0x358637bd
	v_fmac_f32_e32 v8, 0x3b800000, v7
	v_rsq_f32_e32 v8, v8
	s_nop 0
	v_mul_f32_e32 v64, v64, v8
	v_mul_f32_e32 v65, v65, v8
	v_mul_f32_e32 v66, v66, v8
	v_mul_f32_e32 v67, v67, v8
	v_mul_f32_e32 v68, v68, v8
	v_mul_f32_e32 v69, v69, v8
	v_mul_f32_e32 v70, v70, v8
	v_mul_f32_e32 v71, v71, v8
	v_mul_f32_e32 v64, v64, v16
	v_mul_f32_e32 v65, v65, v17
	v_mul_f32_e32 v66, v66, v18
	v_mul_f32_e32 v67, v67, v19
	v_mul_f32_e32 v68, v68, v20
	v_mul_f32_e32 v69, v69, v21
	v_mul_f32_e32 v70, v70, v22
	v_mul_f32_e32 v71, v71, v23
	v_cvt_pk_bf16_f32 v88, v64, v65
	v_cvt_pk_bf16_f32 v89, v66, v67
	v_cvt_pk_bf16_f32 v90, v68, v69
	v_cvt_pk_bf16_f32 v91, v70, v71
	s_nop 0
	global_store_dwordx4 v4, v[88:91], s[80:81] offset:512
	s_add_i32 s28, s27, 2
	s_cmp_lt_u32 s28, s26
	s_cselect_b32 s28, s28, 0
	s_cmp_ge_u32 s28, s23
	s_addc_u32 s44, s28, 0
	s_cmp_ge_u32 s44, s25
	s_addc_u32 s44, s44, 0
	s_lshl_b32 s44, s44, 11
	s_add_i32 s44, s44, s19
	s_lshl_b32 s16, s44, 10
	s_lshl_b32 s17, s44, 11
	s_add_u32 s30, s96, s16
	s_addc_u32 s31, s97, 0
	s_add_u32 s48, s30, 0x3600000
	s_addc_u32 s49, s31, 0
	s_add_u32 s30, s30, 0x5a00000
	s_addc_u32 s31, s31, 0
	s_add_u32 s38, s30, 0x2400000
	s_addc_u32 s39, s31, 0
	s_add_u32 s66, s96, s17
	s_addc_u32 s67, s97, 0
	s_add_u32 s66, s66, 0xea00000
	s_addc_u32 s67, s67, 0
	s_add_u32 s80, s6, s17
	s_addc_u32 s81, s7, 0
	global_load_dwordx4 v[32:35], v4, s[30:31]
	global_load_dwordx4 v[36:39], v4, s[38:39]
	global_load_dwordx4 v[40:43], v4, s[66:67]
	global_load_dwordx4 v[44:47], v4, s[48:49]
	s_waitcnt vmcnt(5)
; DI u32 pack2(float a, float b) { return (u32)f2bf(a) | ((u32)f2bf(b) << 16); }
; DI float bflo(u32 v) { return __uint_as_float(v << 16); }
; DI float bfhi(u32 v) { return __uint_as_float(v & 0xffff0000u); }
; DI float silu_f(float x) { return x / (1.f + __expf(-x)); }
; DI void phase_ssd_combine(const Params& p, int l, int bid, int nblk) {
;     ...
;   for (int row = bid * 4 + w; row < ROWS; row += nblk * 4) {
;     const int pos = row % TPB;
;     if (l == 1 && pos < CTXL) continue;
;     const uint4 vf = *(const uint4*)(YF + (size_t)row * 512 + c0);
;     const uint4 vb = *(const uint4*)(YB + (size_t)row * 512 + c0);
;     const uint4 vx = *(const uint4*)(XBCA + (size_t)row * 1024 + c0);
;     const uint4 vz = *(const uint4*)(PZ + (size_t)row * 512 + c0);
;     const u32 af_[4] = {vf.x, vf.y, vf.z, vf.w}, ab_[4] = {vb.x, vb.y, vb.z, vb.w};
;     const u32 ax_[4] = {vx.x, vx.y, vx.z, vx.w}, az_[4] = {vz.x, vz.y, vz.z, vz.w};
;     float y[8];
;     float ss = 0.f;
; #pragma unroll
;     for (int i = 0; i < 4; ++i) {
;       const float y0 = bflo(af_[i]) + bflo(ab_[i]) + dsk * bflo(ax_[i]);
;       const float y1 = bfhi(af_[i]) + bfhi(ab_[i]) + dsk * bfhi(ax_[i]);
;       y[2 * i] = y0 * silu_f(bflo(az_[i]));
;       y[2 * i + 1] = y1 * silu_f(bfhi(az_[i]));
;       ss += y[2 * i] * y[2 * i] + y[2 * i + 1] * y[2 * i + 1];
;     }
; #pragma unroll
;     for (int o = 16; o >= 1; o >>= 1) ss += __shfl_xor(ss, o);
;     const float rs = rsqrtf(ss * (1.f / 256.f) + EPSF);
;     float o8[8];
; #pragma unroll
;     for (int i = 0; i < 8; ++i) o8[i] = y[i] * rs * ng[c0 + i];
;     uint4 o = {pack2(o8[0], o8[1]), pack2(o8[2], o8[3]), pack2(o8[4], o8[5]), pack2(o8[6], o8[7])};
;     *(uint4*)&YM[(size_t)row * 1024 + 256 + c0] = o;
	v_lshlrev_b32_e32 v64, 16, v48
	v_and_b32_e32 v65, 0xffff0000, v48
	v_lshlrev_b32_e32 v66, 16, v49
	v_and_b32_e32 v67, 0xffff0000, v49
	v_lshlrev_b32_e32 v68, 16, v50
	v_and_b32_e32 v69, 0xffff0000, v50
	v_lshlrev_b32_e32 v70, 16, v51
	v_and_b32_e32 v71, 0xffff0000, v51
	v_lshlrev_b32_e32 v80, 16, v52
	v_and_b32_e32 v81, 0xffff0000, v52
	v_lshlrev_b32_e32 v82, 16, v53
	v_and_b32_e32 v83, 0xffff0000, v53
	v_lshlrev_b32_e32 v84, 16, v54
	v_and_b32_e32 v85, 0xffff0000, v54
	v_lshlrev_b32_e32 v86, 16, v55
	v_and_b32_e32 v87, 0xffff0000, v55
	v_add_f32_e32 v64, v64, v80
	v_add_f32_e32 v65, v65, v81
	v_add_f32_e32 v66, v66, v82
	v_add_f32_e32 v67, v67, v83
	v_add_f32_e32 v68, v68, v84
	v_add_f32_e32 v69, v69, v85
	v_add_f32_e32 v70, v70, v86
	v_add_f32_e32 v71, v71, v87
	v_lshlrev_b32_e32 v80, 16, v56
	v_and_b32_e32 v81, 0xffff0000, v56
	v_lshlrev_b32_e32 v82, 16, v57
	v_and_b32_e32 v83, 0xffff0000, v57
	v_lshlrev_b32_e32 v84, 16, v58
	v_and_b32_e32 v85, 0xffff0000, v58
	v_lshlrev_b32_e32 v86, 16, v59
	v_and_b32_e32 v87, 0xffff0000, v59
	v_fmac_f32_e32 v64, v24, v80
	v_fmac_f32_e32 v65, v24, v81
	v_fmac_f32_e32 v66, v24, v82
	v_fmac_f32_e32 v67, v24, v83
	v_fmac_f32_e32 v68, v24, v84
	v_fmac_f32_e32 v69, v24, v85
	v_fmac_f32_e32 v70, v24, v86
	v_fmac_f32_e32 v71, v24, v87
	v_lshlrev_b32_e32 v72, 16, v60
	v_and_b32_e32 v73, 0xffff0000, v60
	v_lshlrev_b32_e32 v74, 16, v61
	v_and_b32_e32 v75, 0xffff0000, v61
	v_lshlrev_b32_e32 v76, 16, v62
	v_and_b32_e32 v77, 0xffff0000, v62
	v_lshlrev_b32_e32 v78, 16, v63
	v_and_b32_e32 v79, 0xffff0000, v63
	v_mul_f32_e32 v80, 0xbfb8aa3b, v72
	v_mul_f32_e32 v81, 0xbfb8aa3b, v73
	v_mul_f32_e32 v82, 0xbfb8aa3b, v74
	v_mul_f32_e32 v83, 0xbfb8aa3b, v75
	v_mul_f32_e32 v84, 0xbfb8aa3b, v76
	v_mul_f32_e32 v85, 0xbfb8aa3b, v77
	v_mul_f32_e32 v86, 0xbfb8aa3b, v78
	v_mul_f32_e32 v87, 0xbfb8aa3b, v79
	v_exp_f32_e32 v80, v80
	v_exp_f32_e32 v81, v81
	v_exp_f32_e32 v82, v82
	v_exp_f32_e32 v83, v83
	v_exp_f32_e32 v84, v84
	v_exp_f32_e32 v85, v85
	v_exp_f32_e32 v86, v86
	v_exp_f32_e32 v87, v87
	v_add_f32_e32 v80, 1.0, v80
	v_add_f32_e32 v81, 1.0, v81
	v_add_f32_e32 v82, 1.0, v82
	v_add_f32_e32 v83, 1.0, v83
	v_add_f32_e32 v84, 1.0, v84
	v_add_f32_e32 v85, 1.0, v85
	v_add_f32_e32 v86, 1.0, v86
	v_add_f32_e32 v87, 1.0, v87
	v_rcp_f32_e32 v80, v80
	v_rcp_f32_e32 v81, v81
	v_rcp_f32_e32 v82, v82
	v_rcp_f32_e32 v83, v83
	v_rcp_f32_e32 v84, v84
	v_rcp_f32_e32 v85, v85
	v_rcp_f32_e32 v86, v86
	v_rcp_f32_e32 v87, v87
	v_mul_f32_e32 v72, v72, v80
	v_mul_f32_e32 v73, v73, v81
	v_mul_f32_e32 v74, v74, v82
	v_mul_f32_e32 v75, v75, v83
	v_mul_f32_e32 v76, v76, v84
	v_mul_f32_e32 v77, v77, v85
	v_mul_f32_e32 v78, v78, v86
	v_mul_f32_e32 v79, v79, v87
	v_mul_f32_e32 v64, v64, v72
	v_mul_f32_e32 v65, v65, v73
	v_mul_f32_e32 v66, v66, v74
	v_mul_f32_e32 v67, v67, v75
	v_mul_f32_e32 v68, v68, v76
	v_mul_f32_e32 v69, v69, v77
	v_mul_f32_e32 v70, v70, v78
	v_mul_f32_e32 v71, v71, v79
	v_mul_f32_e32 v7, v64, v64
	v_fmac_f32_e32 v7, v65, v65
	v_fmac_f32_e32 v7, v66, v66
	v_fmac_f32_e32 v7, v67, v67
	v_fmac_f32_e32 v7, v68, v68
	v_fmac_f32_e32 v7, v69, v69
	v_fmac_f32_e32 v7, v70, v70
	v_fmac_f32_e32 v7, v71, v71
	s_nop 1
	v_add_f32_dpp v7, v7, v7 quad_perm:[1,0,3,2] row_mask:0xf bank_mask:0xf
	s_nop 1
	v_add_f32_dpp v7, v7, v7 quad_perm:[2,3,0,1] row_mask:0xf bank_mask:0xf
	s_nop 1
	v_add_f32_dpp v7, v7, v7 row_half_mirror row_mask:0xf bank_mask:0xf
	s_nop 1
	v_add_f32_dpp v7, v7, v7 row_mirror row_mask:0xf bank_mask:0xf
	s_nop 1
	ds_bpermute_b32 v8, v5, v7
	s_waitcnt lgkmcnt(0)
	v_add_f32_e32 v7, v7, v8
	v_mov_b32_e32 v8, 0x358637bd
	v_fmac_f32_e32 v8, 0x3b800000, v7
	v_rsq_f32_e32 v8, v8
	s_nop 0
	v_mul_f32_e32 v64, v64, v8
	v_mul_f32_e32 v65, v65, v8
	v_mul_f32_e32 v66, v66, v8
	v_mul_f32_e32 v67, v67, v8
	v_mul_f32_e32 v68, v68, v8
	v_mul_f32_e32 v69, v69, v8
	v_mul_f32_e32 v70, v70, v8
	v_mul_f32_e32 v71, v71, v8
	v_mul_f32_e32 v64, v64, v16
	v_mul_f32_e32 v65, v65, v17
	v_mul_f32_e32 v66, v66, v18
	v_mul_f32_e32 v67, v67, v19
	v_mul_f32_e32 v68, v68, v20
	v_mul_f32_e32 v69, v69, v21
	v_mul_f32_e32 v70, v70, v22
	v_mul_f32_e32 v71, v71, v23
	v_cvt_pk_bf16_f32 v88, v64, v65
	v_cvt_pk_bf16_f32 v89, v66, v67
	v_cvt_pk_bf16_f32 v90, v68, v69
	v_cvt_pk_bf16_f32 v91, v70, v71
	s_nop 0
	global_store_dwordx4 v4, v[88:91], s[82:83] offset:512
	s_add_i32 s28, s27, 3
	s_cmp_lt_u32 s28, s26
	s_cselect_b32 s28, s28, 0
	s_cmp_ge_u32 s28, s23
	s_addc_u32 s44, s28, 0
	s_cmp_ge_u32 s44, s25
	s_addc_u32 s44, s44, 0
	s_lshl_b32 s44, s44, 11
	s_add_i32 s44, s44, s19
	s_lshl_b32 s16, s44, 10
	s_lshl_b32 s17, s44, 11
	s_add_u32 s30, s96, s16
	s_addc_u32 s31, s97, 0
	s_add_u32 s48, s30, 0x3600000
	s_addc_u32 s49, s31, 0
	s_add_u32 s30, s30, 0x5a00000
	s_addc_u32 s31, s31, 0
	s_add_u32 s38, s30, 0x2400000
	s_addc_u32 s39, s31, 0
	s_add_u32 s66, s96, s17
	s_addc_u32 s67, s97, 0
	s_add_u32 s66, s66, 0xea00000
	s_addc_u32 s67, s67, 0
	s_add_u32 s82, s6, s17
	s_addc_u32 s83, s7, 0
	global_load_dwordx4 v[48:51], v4, s[30:31]
	global_load_dwordx4 v[52:55], v4, s[38:39]
	global_load_dwordx4 v[56:59], v4, s[66:67]
	global_load_dwordx4 v[60:63], v4, s[48:49]
	s_add_i32 s27, s27, 2
	s_cmp_lt_u32 s27, s26
	s_cbranch_scc1 .Lcmb_top
; DI u16 f2bf(float x) { u32 u = __float_as_uint(x); u += 0x7fffu + ((u >> 16) & 1u); return (u16)(u >> 16); }
; DI float bf2f(u16 v) { return __uint_as_float(((u32)v) << 16); }
; DI void hyena_item_lat(const Params& p, int l, int it) {
;     ...
; #pragma unroll
;   for (int i = 0; i < 8; ++i)
; #pragma unroll
;     for (int r = 0; r < 4; ++r) {
;       const int t = tt0 + 16 * i + kg * 4 + r;
;       const size_t row = (size_t)b * TPB + posoff + t;
;       const float uu = bf2f(UT[((size_t)(c * 16 + b)) * TPB + posoff + t]);
;       const float x1 = bf2f(X1C[row * 256 + c]);
;       YM[row * 1024 + c] = f2bf(x1 * (scale * acc[i][r] + bias * uu));
;     }
	s_waitcnt vmcnt(0)
	v_readlane_b32 s19, v253, 0
	v_lshrrev_b32_e32 v4, 2, v218
	v_and_b32_e32 v5, 3, v218
	v_lshlrev_b32_e32 v6, 17, v4
	v_lshl_add_u32 v6, v5, 4, v6
	v_mul_u32_u24_e32 v7, 1088, v5
	v_lshl_add_u32 v7, v4, 2, v7
	v_mul_u32_u24_e32 v8, 272, v4
	v_lshl_add_u32 v8, v5, 6, v8
	v_lshlrev_b32_e32 v9, 9, v4
	v_lshl_add_u32 v9, v5, 5, v9
	v_lshlrev_b32_e32 v10, 11, v4
	v_lshl_add_u32 v10, v5, 5, v10
	v_lshlrev_b32_e32 v12, 14, v4
	v_lshl_add_u32 v12, v5, 4, v12
	s_mov_b32 s16, s19
	s_and_b32 s22, s16, 3
	s_bfe_u32 s23, s16, 0x50002
	s_lshr_b32 s25, s16, 7
	s_lshl_b32 s17, s22, 23
	s_lshl_b32 s16, s25, 13
	s_add_i32 s17, s17, s16
	s_lshl_b32 s16, s23, 8
	s_add_i32 s17, s17, s16
	s_add_u32 s26, s96, s17
	s_addc_u32 s27, s97, 0
	s_mul_i32 s17, s25, 0x900
	s_lshl_b32 s16, s23, 6
	s_add_i32 s17, s17, s16
	s_addk_i32 s17, 0x100
	s_lshl_b32 s16, s17, 9
	s_lshl_b32 s39, s22, 7
	s_add_i32 s16, s16, s39
	s_add_u32 s28, s96, 0x16800000
	s_addc_u32 s29, s97, 0
	s_add_u32 s28, s28, s16
	s_addc_u32 s29, s29, 0
	s_lshl_b32 s16, s17, 11
	s_add_i32 s16, s16, s39
	s_add_u32 s30, s6, s16
	s_addc_u32 s31, s7, 0
	global_load_dwordx4 v[16:19], v6, s[26:27]
	global_load_dwordx4 v[20:23], v6, s[26:27] offset:64
	global_load_dwordx4 v[24:27], v6, s[26:27] offset:128
	global_load_dwordx4 v[28:31], v6, s[26:27] offset:192
	global_load_dwordx4 v[32:35], v9, s[28:29]
	global_load_dwordx4 v[36:39], v9, s[28:29] offset:16
	s_add_i32 s16, s19, 0x200
	s_and_b32 s22, s16, 3
	s_bfe_u32 s23, s16, 0x50002
	s_lshr_b32 s25, s16, 7
	s_lshl_b32 s17, s22, 23
	s_lshl_b32 s16, s25, 13
	s_add_i32 s17, s17, s16
	s_lshl_b32 s16, s23, 8
	s_add_i32 s17, s17, s16
	s_add_u32 s48, s96, s17
	s_addc_u32 s49, s97, 0
	s_mul_i32 s17, s25, 0x900
	s_lshl_b32 s16, s23, 6
	s_add_i32 s17, s17, s16
	s_addk_i32 s17, 0x100
	s_lshl_b32 s16, s17, 9
	s_lshl_b32 s39, s22, 7
	s_add_i32 s16, s16, s39
	s_add_u32 s50, s96, 0x16800000
	s_addc_u32 s51, s97, 0
	s_add_u32 s50, s50, s16
	s_addc_u32 s51, s51, 0
	s_lshl_b32 s16, s17, 11
	s_add_i32 s16, s16, s39
	s_add_u32 s56, s6, s16
	s_addc_u32 s57, s7, 0
	global_load_dwordx4 v[40:43], v6, s[48:49]
	global_load_dwordx4 v[44:47], v6, s[48:49] offset:64
	global_load_dwordx4 v[48:51], v6, s[48:49] offset:128
	global_load_dwordx4 v[52:55], v6, s[48:49] offset:192
	global_load_dwordx4 v[56:59], v9, s[50:51]
	global_load_dwordx4 v[60:63], v9, s[50:51] offset:16
	s_waitcnt vmcnt(8)
	ds_write_b32 v7, v16
	ds_write_b32 v7, v17 offset:272
	ds_write_b32 v7, v18 offset:544
	ds_write_b32 v7, v19 offset:816
	ds_write_b32 v7, v20 offset:4352
	ds_write_b32 v7, v21 offset:4624
	ds_write_b32 v7, v22 offset:4896
	ds_write_b32 v7, v23 offset:5168
	ds_write_b32 v7, v24 offset:8704
	ds_write_b32 v7, v25 offset:8976
	ds_write_b32 v7, v26 offset:9248
	ds_write_b32 v7, v27 offset:9520
	ds_write_b32 v7, v28 offset:13056
	ds_write_b32 v7, v29 offset:13328
	ds_write_b32 v7, v30 offset:13600
	ds_write_b32 v7, v31 offset:13872
	s_waitcnt lgkmcnt(0)
	s_barrier
	ds_read_b128 v[16:19], v8
	ds_read_b128 v[20:23], v8 offset:16
	ds_read_b128 v[24:27], v8 offset:32
	ds_read_b128 v[28:31], v8 offset:48
	s_waitcnt vmcnt(6) lgkmcnt(0)
	v_lshlrev_b32_e32 v11, 16, v32
	v_mul_f32_e32 v16, v16, v11
	v_and_b32_e32 v11, 0xffff0000, v32
	v_mul_f32_e32 v17, v17, v11
	v_lshlrev_b32_e32 v11, 16, v33
	v_mul_f32_e32 v18, v18, v11
	v_and_b32_e32 v11, 0xffff0000, v33
	v_mul_f32_e32 v19, v19, v11
	v_lshlrev_b32_e32 v11, 16, v34
	v_mul_f32_e32 v20, v20, v11
	v_and_b32_e32 v11, 0xffff0000, v34
	v_mul_f32_e32 v21, v21, v11
	v_lshlrev_b32_e32 v11, 16, v35
	v_mul_f32_e32 v22, v22, v11
	v_and_b32_e32 v11, 0xffff0000, v35
	v_mul_f32_e32 v23, v23, v11
	v_lshlrev_b32_e32 v11, 16, v36
	v_mul_f32_e32 v24, v24, v11
	v_and_b32_e32 v11, 0xffff0000, v36
	v_mul_f32_e32 v25, v25, v11
	v_lshlrev_b32_e32 v11, 16, v37
	v_mul_f32_e32 v26, v26, v11
	v_and_b32_e32 v11, 0xffff0000, v37
	v_mul_f32_e32 v27, v27, v11
	v_lshlrev_b32_e32 v11, 16, v38
	v_mul_f32_e32 v28, v28, v11
	v_and_b32_e32 v11, 0xffff0000, v38
	v_mul_f32_e32 v29, v29, v11
	v_lshlrev_b32_e32 v11, 16, v39
	v_mul_f32_e32 v30, v30, v11
	v_and_b32_e32 v11, 0xffff0000, v39
	v_mul_f32_e32 v31, v31, v11
	v_cvt_pk_bf16_f32 v32, v16, v17
	v_cvt_pk_bf16_f32 v33, v18, v19
	v_cvt_pk_bf16_f32 v34, v20, v21
	v_cvt_pk_bf16_f32 v35, v22, v23
	v_cvt_pk_bf16_f32 v36, v24, v25
	v_cvt_pk_bf16_f32 v37, v26, v27
	v_cvt_pk_bf16_f32 v38, v28, v29
	v_cvt_pk_bf16_f32 v39, v30, v31
	s_nop 0
	global_store_dwordx4 v10, v[32:35], s[30:31]
	global_store_dwordx4 v10, v[36:39], s[30:31] offset:16
	s_barrier
	s_add_i32 s16, s19, 0x400
	s_and_b32 s22, s16, 3
	s_bfe_u32 s23, s16, 0x50002
	s_lshr_b32 s25, s16, 7
	s_lshl_b32 s17, s22, 23
	s_lshl_b32 s16, s25, 13
	s_add_i32 s17, s17, s16
	s_lshl_b32 s16, s23, 8
	s_add_i32 s17, s17, s16
	s_add_u32 s26, s96, s17
	s_addc_u32 s27, s97, 0
	s_mul_i32 s17, s25, 0x900
	s_lshl_b32 s16, s23, 6
	s_add_i32 s17, s17, s16
	s_addk_i32 s17, 0x100
	s_lshl_b32 s16, s17, 9
	s_lshl_b32 s39, s22, 7
	s_add_i32 s16, s16, s39
	s_add_u32 s28, s96, 0x16800000
	s_addc_u32 s29, s97, 0
	s_add_u32 s28, s28, s16
	s_addc_u32 s29, s29, 0
	s_lshl_b32 s16, s17, 11
	s_add_i32 s16, s16, s39
	s_add_u32 s30, s6, s16
	s_addc_u32 s31, s7, 0
	global_load_dwordx4 v[16:19], v6, s[26:27]
	global_load_dwordx4 v[20:23], v6, s[26:27] offset:64
	global_load_dwordx4 v[24:27], v6, s[26:27] offset:128
	global_load_dwordx4 v[28:31], v6, s[26:27] offset:192
	global_load_dwordx4 v[32:35], v9, s[28:29]
	global_load_dwordx4 v[36:39], v9, s[28:29] offset:16
	s_waitcnt vmcnt(10)
	ds_write_b32 v7, v40
	ds_write_b32 v7, v41 offset:272
	ds_write_b32 v7, v42 offset:544
	ds_write_b32 v7, v43 offset:816
	ds_write_b32 v7, v44 offset:4352
	ds_write_b32 v7, v45 offset:4624
	ds_write_b32 v7, v46 offset:4896
	ds_write_b32 v7, v47 offset:5168
	ds_write_b32 v7, v48 offset:8704
	ds_write_b32 v7, v49 offset:8976
	ds_write_b32 v7, v50 offset:9248
	ds_write_b32 v7, v51 offset:9520
	ds_write_b32 v7, v52 offset:13056
	ds_write_b32 v7, v53 offset:13328
	ds_write_b32 v7, v54 offset:13600
	ds_write_b32 v7, v55 offset:13872
	s_waitcnt lgkmcnt(0)
	s_barrier
; DI u16 f2bf(float x) { u32 u = __float_as_uint(x); u += 0x7fffu + ((u >> 16) & 1u); return (u16)(u >> 16); }
; DI float bf2f(u16 v) { return __uint_as_float(((u32)v) << 16); }
; DI void hyena_item_lat(const Params& p, int l, int it) {
;     ...
; #pragma unroll
;   for (int i = 0; i < 8; ++i)
; #pragma unroll
;     for (int r = 0; r < 4; ++r) {
;       const int t = tt0 + 16 * i + kg * 4 + r;
;       const size_t row = (size_t)b * TPB + posoff + t;
;       const float uu = bf2f(UT[((size_t)(c * 16 + b)) * TPB + posoff + t]);
;       const float x1 = bf2f(X1C[row * 256 + c]);
;       YM[row * 1024 + c] = f2bf(x1 * (scale * acc[i][r] + bias * uu));
;     }
	ds_read_b128 v[40:43], v8
	ds_read_b128 v[44:47], v8 offset:16
	ds_read_b128 v[48:51], v8 offset:32
	ds_read_b128 v[52:55], v8 offset:48
	s_waitcnt vmcnt(8) lgkmcnt(0)
	v_lshlrev_b32_e32 v11, 16, v56
	v_mul_f32_e32 v40, v40, v11
	v_and_b32_e32 v11, 0xffff0000, v56
	v_mul_f32_e32 v41, v41, v11
	v_lshlrev_b32_e32 v11, 16, v57
	v_mul_f32_e32 v42, v42, v11
	v_and_b32_e32 v11, 0xffff0000, v57
	v_mul_f32_e32 v43, v43, v11
	v_lshlrev_b32_e32 v11, 16, v58
	v_mul_f32_e32 v44, v44, v11
	v_and_b32_e32 v11, 0xffff0000, v58
	v_mul_f32_e32 v45, v45, v11
	v_lshlrev_b32_e32 v11, 16, v59
	v_mul_f32_e32 v46, v46, v11
	v_and_b32_e32 v11, 0xffff0000, v59
	v_mul_f32_e32 v47, v47, v11
	v_lshlrev_b32_e32 v11, 16, v60
	v_mul_f32_e32 v48, v48, v11
	v_and_b32_e32 v11, 0xffff0000, v60
	v_mul_f32_e32 v49, v49, v11
	v_lshlrev_b32_e32 v11, 16, v61
	v_mul_f32_e32 v50, v50, v11
	v_and_b32_e32 v11, 0xffff0000, v61
	v_mul_f32_e32 v51, v51, v11
	v_lshlrev_b32_e32 v11, 16, v62
	v_mul_f32_e32 v52, v52, v11
	v_and_b32_e32 v11, 0xffff0000, v62
	v_mul_f32_e32 v53, v53, v11
	v_lshlrev_b32_e32 v11, 16, v63
	v_mul_f32_e32 v54, v54, v11
	v_and_b32_e32 v11, 0xffff0000, v63
	v_mul_f32_e32 v55, v55, v11
	v_cvt_pk_bf16_f32 v56, v40, v41
	v_cvt_pk_bf16_f32 v57, v42, v43
	v_cvt_pk_bf16_f32 v58, v44, v45
	v_cvt_pk_bf16_f32 v59, v46, v47
	v_cvt_pk_bf16_f32 v60, v48, v49
	v_cvt_pk_bf16_f32 v61, v50, v51
	v_cvt_pk_bf16_f32 v62, v52, v53
	v_cvt_pk_bf16_f32 v63, v54, v55
	s_nop 0
	global_store_dwordx4 v10, v[56:59], s[56:57]
	global_store_dwordx4 v10, v[60:63], s[56:57] offset:16
	s_barrier
	s_add_i32 s16, s19, 0x600
	s_and_b32 s22, s16, 3
	s_bfe_u32 s23, s16, 0x50002
	s_lshr_b32 s25, s16, 7
	s_lshl_b32 s17, s22, 23
	s_lshl_b32 s16, s25, 13
	s_add_i32 s17, s17, s16
	s_lshl_b32 s16, s23, 8
	s_add_i32 s17, s17, s16
	s_add_u32 s48, s96, s17
	s_addc_u32 s49, s97, 0
	s_mul_i32 s17, s25, 0x900
	s_lshl_b32 s16, s23, 6
	s_add_i32 s17, s17, s16
	s_addk_i32 s17, 0x100
	s_lshl_b32 s16, s17, 9
	s_lshl_b32 s39, s22, 7
	s_add_i32 s16, s16, s39
	s_add_u32 s50, s96, 0x16800000
	s_addc_u32 s51, s97, 0
	s_add_u32 s50, s50, s16
	s_addc_u32 s51, s51, 0
	s_lshl_b32 s16, s17, 11
	s_add_i32 s16, s16, s39
	s_add_u32 s56, s6, s16
	s_addc_u32 s57, s7, 0
	global_load_dwordx4 v[40:43], v6, s[48:49]
	global_load_dwordx4 v[44:47], v6, s[48:49] offset:64
	global_load_dwordx4 v[48:51], v6, s[48:49] offset:128
	global_load_dwordx4 v[52:55], v6, s[48:49] offset:192
	global_load_dwordx4 v[56:59], v9, s[50:51]
	global_load_dwordx4 v[60:63], v9, s[50:51] offset:16
	s_waitcnt vmcnt(10)
	ds_write_b32 v7, v16
	ds_write_b32 v7, v17 offset:272
	ds_write_b32 v7, v18 offset:544
	ds_write_b32 v7, v19 offset:816
	ds_write_b32 v7, v20 offset:4352
	ds_write_b32 v7, v21 offset:4624
	ds_write_b32 v7, v22 offset:4896
	ds_write_b32 v7, v23 offset:5168
	ds_write_b32 v7, v24 offset:8704
	ds_write_b32 v7, v25 offset:8976
	ds_write_b32 v7, v26 offset:9248
	ds_write_b32 v7, v27 offset:9520
	ds_write_b32 v7, v28 offset:13056
	ds_write_b32 v7, v29 offset:13328
	ds_write_b32 v7, v30 offset:13600
	ds_write_b32 v7, v31 offset:13872
	s_waitcnt lgkmcnt(0)
	s_barrier
	ds_read_b128 v[16:19], v8
	ds_read_b128 v[20:23], v8 offset:16
	ds_read_b128 v[24:27], v8 offset:32
	ds_read_b128 v[28:31], v8 offset:48
	s_waitcnt vmcnt(8) lgkmcnt(0)
	v_lshlrev_b32_e32 v11, 16, v32
	v_mul_f32_e32 v16, v16, v11
	v_and_b32_e32 v11, 0xffff0000, v32
	v_mul_f32_e32 v17, v17, v11
	v_lshlrev_b32_e32 v11, 16, v33
	v_mul_f32_e32 v18, v18, v11
	v_and_b32_e32 v11, 0xffff0000, v33
	v_mul_f32_e32 v19, v19, v11
	v_lshlrev_b32_e32 v11, 16, v34
	v_mul_f32_e32 v20, v20, v11
	v_and_b32_e32 v11, 0xffff0000, v34
	v_mul_f32_e32 v21, v21, v11
	v_lshlrev_b32_e32 v11, 16, v35
	v_mul_f32_e32 v22, v22, v11
	v_and_b32_e32 v11, 0xffff0000, v35
	v_mul_f32_e32 v23, v23, v11
	v_lshlrev_b32_e32 v11, 16, v36
	v_mul_f32_e32 v24, v24, v11
	v_and_b32_e32 v11, 0xffff0000, v36
	v_mul_f32_e32 v25, v25, v11
	v_lshlrev_b32_e32 v11, 16, v37
	v_mul_f32_e32 v26, v26, v11
	v_and_b32_e32 v11, 0xffff0000, v37
	v_mul_f32_e32 v27, v27, v11
	v_lshlrev_b32_e32 v11, 16, v38
	v_mul_f32_e32 v28, v28, v11
	v_and_b32_e32 v11, 0xffff0000, v38
	v_mul_f32_e32 v29, v29, v11
	v_lshlrev_b32_e32 v11, 16, v39
	v_mul_f32_e32 v30, v30, v11
	v_and_b32_e32 v11, 0xffff0000, v39
	v_mul_f32_e32 v31, v31, v11
	v_cvt_pk_bf16_f32 v32, v16, v17
	v_cvt_pk_bf16_f32 v33, v18, v19
	v_cvt_pk_bf16_f32 v34, v20, v21
	v_cvt_pk_bf16_f32 v35, v22, v23
	v_cvt_pk_bf16_f32 v36, v24, v25
	v_cvt_pk_bf16_f32 v37, v26, v27
	v_cvt_pk_bf16_f32 v38, v28, v29
	v_cvt_pk_bf16_f32 v39, v30, v31
	s_nop 0
	global_store_dwordx4 v10, v[32:35], s[30:31]
	global_store_dwordx4 v10, v[36:39], s[30:31] offset:16
	s_barrier
	s_cmpk_lt_u32 s19, 0x100
	s_cbranch_scc0 .Lhyt_last
	s_and_b32 s22, s19, 3
	s_bfe_u32 s23, s19, 0x20002
	s_lshr_b32 s25, s19, 4
	s_lshl_b32 s17, s22, 20
	s_lshl_b32 s16, s25, 10
	s_add_i32 s17, s17, s16
	s_lshl_b32 s16, s23, 8
	s_add_i32 s17, s17, s16
	s_add_u32 s17, s17, 0x2000000
	s_add_u32 s26, s96, s17
	s_addc_u32 s27, s97, 0
	s_mul_i32 s17, s25, 0x900
	s_lshl_b32 s16, s23, 6
	s_add_i32 s17, s17, s16
	s_lshl_b32 s16, s17, 9
	s_lshl_b32 s39, s22, 7
	s_add_i32 s16, s16, s39
	s_add_u32 s28, s96, 0x16800000
	s_addc_u32 s29, s97, 0
	s_add_u32 s28, s28, s16
	s_addc_u32 s29, s29, 0
	s_lshl_b32 s16, s17, 11
	s_add_i32 s16, s16, s39
	s_add_u32 s30, s6, s16
	s_addc_u32 s31, s7, 0
	global_load_dwordx4 v[16:19], v12, s[26:27]
	global_load_dwordx4 v[20:23], v12, s[26:27] offset:64
	global_load_dwordx4 v[24:27], v12, s[26:27] offset:128
	global_load_dwordx4 v[28:31], v12, s[26:27] offset:192
	global_load_dwordx4 v[32:35], v9, s[28:29]
	global_load_dwordx4 v[36:39], v9, s[28:29] offset:16
	s_waitcnt vmcnt(10)
	ds_write_b32 v7, v40
	ds_write_b32 v7, v41 offset:272
	ds_write_b32 v7, v42 offset:544
	ds_write_b32 v7, v43 offset:816
	ds_write_b32 v7, v44 offset:4352
	ds_write_b32 v7, v45 offset:4624
	ds_write_b32 v7, v46 offset:4896
	ds_write_b32 v7, v47 offset:5168
	ds_write_b32 v7, v48 offset:8704
	ds_write_b32 v7, v49 offset:8976
	ds_write_b32 v7, v50 offset:9248
	ds_write_b32 v7, v51 offset:9520
	ds_write_b32 v7, v52 offset:13056
	ds_write_b32 v7, v53 offset:13328
	ds_write_b32 v7, v54 offset:13600
	ds_write_b32 v7, v55 offset:13872
	s_waitcnt lgkmcnt(0)
	s_barrier
; DI u16 f2bf(float x) { u32 u = __float_as_uint(x); u += 0x7fffu + ((u >> 16) & 1u); return (u16)(u >> 16); }
; DI float bf2f(u16 v) { return __uint_as_float(((u32)v) << 16); }
; DI void hyena_item_lat(const Params& p, int l, int it) {
;     ...
; #pragma unroll
;   for (int i = 0; i < 8; ++i)
; #pragma unroll
;     for (int r = 0; r < 4; ++r) {
;       const int t = tt0 + 16 * i + kg * 4 + r;
;       const size_t row = (size_t)b * TPB + posoff + t;
;       const float uu = bf2f(UT[((size_t)(c * 16 + b)) * TPB + posoff + t]);
;       const float x1 = bf2f(X1C[row * 256 + c]);
;       YM[row * 1024 + c] = f2bf(x1 * (scale * acc[i][r] + bias * uu));
;     }
	ds_read_b128 v[40:43], v8
	ds_read_b128 v[44:47], v8 offset:16
	ds_read_b128 v[48:51], v8 offset:32
	ds_read_b128 v[52:55], v8 offset:48
	s_waitcnt vmcnt(8) lgkmcnt(0)
	v_lshlrev_b32_e32 v11, 16, v56
	v_mul_f32_e32 v40, v40, v11
	v_and_b32_e32 v11, 0xffff0000, v56
	v_mul_f32_e32 v41, v41, v11
	v_lshlrev_b32_e32 v11, 16, v57
	v_mul_f32_e32 v42, v42, v11
	v_and_b32_e32 v11, 0xffff0000, v57
	v_mul_f32_e32 v43, v43, v11
	v_lshlrev_b32_e32 v11, 16, v58
	v_mul_f32_e32 v44, v44, v11
	v_and_b32_e32 v11, 0xffff0000, v58
	v_mul_f32_e32 v45, v45, v11
	v_lshlrev_b32_e32 v11, 16, v59
	v_mul_f32_e32 v46, v46, v11
	v_and_b32_e32 v11, 0xffff0000, v59
	v_mul_f32_e32 v47, v47, v11
	v_lshlrev_b32_e32 v11, 16, v60
	v_mul_f32_e32 v48, v48, v11
	v_and_b32_e32 v11, 0xffff0000, v60
	v_mul_f32_e32 v49, v49, v11
	v_lshlrev_b32_e32 v11, 16, v61
	v_mul_f32_e32 v50, v50, v11
	v_and_b32_e32 v11, 0xffff0000, v61
	v_mul_f32_e32 v51, v51, v11
	v_lshlrev_b32_e32 v11, 16, v62
	v_mul_f32_e32 v52, v52, v11
	v_and_b32_e32 v11, 0xffff0000, v62
	v_mul_f32_e32 v53, v53, v11
	v_lshlrev_b32_e32 v11, 16, v63
	v_mul_f32_e32 v54, v54, v11
	v_and_b32_e32 v11, 0xffff0000, v63
	v_mul_f32_e32 v55, v55, v11
	v_cvt_pk_bf16_f32 v56, v40, v41
	v_cvt_pk_bf16_f32 v57, v42, v43
	v_cvt_pk_bf16_f32 v58, v44, v45
	v_cvt_pk_bf16_f32 v59, v46, v47
	v_cvt_pk_bf16_f32 v60, v48, v49
	v_cvt_pk_bf16_f32 v61, v50, v51
	v_cvt_pk_bf16_f32 v62, v52, v53
	v_cvt_pk_bf16_f32 v63, v54, v55
	s_nop 0
	global_store_dwordx4 v10, v[56:59], s[56:57]
	global_store_dwordx4 v10, v[60:63], s[56:57] offset:16
	s_barrier
	s_waitcnt vmcnt(4)
	ds_write_b32 v7, v16
	ds_write_b32 v7, v17 offset:272
	ds_write_b32 v7, v18 offset:544
	ds_write_b32 v7, v19 offset:816
	ds_write_b32 v7, v20 offset:4352
	ds_write_b32 v7, v21 offset:4624
	ds_write_b32 v7, v22 offset:4896
	ds_write_b32 v7, v23 offset:5168
	ds_write_b32 v7, v24 offset:8704
	ds_write_b32 v7, v25 offset:8976
	ds_write_b32 v7, v26 offset:9248
	ds_write_b32 v7, v27 offset:9520
	ds_write_b32 v7, v28 offset:13056
	ds_write_b32 v7, v29 offset:13328
	ds_write_b32 v7, v30 offset:13600
	ds_write_b32 v7, v31 offset:13872
	s_waitcnt lgkmcnt(0)
	s_barrier
	ds_read_b128 v[16:19], v8
	ds_read_b128 v[20:23], v8 offset:16
	ds_read_b128 v[24:27], v8 offset:32
	ds_read_b128 v[28:31], v8 offset:48
	s_waitcnt vmcnt(2) lgkmcnt(0)
	v_lshlrev_b32_e32 v11, 16, v32
	v_mul_f32_e32 v16, v16, v11
	v_and_b32_e32 v11, 0xffff0000, v32
	v_mul_f32_e32 v17, v17, v11
	v_lshlrev_b32_e32 v11, 16, v33
	v_mul_f32_e32 v18, v18, v11
	v_and_b32_e32 v11, 0xffff0000, v33
	v_mul_f32_e32 v19, v19, v11
	v_lshlrev_b32_e32 v11, 16, v34
	v_mul_f32_e32 v20, v20, v11
	v_and_b32_e32 v11, 0xffff0000, v34
	v_mul_f32_e32 v21, v21, v11
	v_lshlrev_b32_e32 v11, 16, v35
	v_mul_f32_e32 v22, v22, v11
	v_and_b32_e32 v11, 0xffff0000, v35
	v_mul_f32_e32 v23, v23, v11
	v_lshlrev_b32_e32 v11, 16, v36
	v_mul_f32_e32 v24, v24, v11
	v_and_b32_e32 v11, 0xffff0000, v36
	v_mul_f32_e32 v25, v25, v11
	v_lshlrev_b32_e32 v11, 16, v37
	v_mul_f32_e32 v26, v26, v11
	v_and_b32_e32 v11, 0xffff0000, v37
	v_mul_f32_e32 v27, v27, v11
	v_lshlrev_b32_e32 v11, 16, v38
	v_mul_f32_e32 v28, v28, v11
	v_and_b32_e32 v11, 0xffff0000, v38
	v_mul_f32_e32 v29, v29, v11
	v_lshlrev_b32_e32 v11, 16, v39
	v_mul_f32_e32 v30, v30, v11
	v_and_b32_e32 v11, 0xffff0000, v39
	v_mul_f32_e32 v31, v31, v11
	v_cvt_pk_bf16_f32 v32, v16, v17
	v_cvt_pk_bf16_f32 v33, v18, v19
	v_cvt_pk_bf16_f32 v34, v20, v21
	v_cvt_pk_bf16_f32 v35, v22, v23
	v_cvt_pk_bf16_f32 v36, v24, v25
	v_cvt_pk_bf16_f32 v37, v26, v27
	v_cvt_pk_bf16_f32 v38, v28, v29
	v_cvt_pk_bf16_f32 v39, v30, v31
	s_nop 0
	global_store_dwordx4 v10, v[32:35], s[30:31]
	global_store_dwordx4 v10, v[36:39], s[30:31] offset:16
	s_barrier
	s_branch .Lhyt_done
.Lhyt_last:
	s_waitcnt vmcnt(4)
	ds_write_b32 v7, v40
	ds_write_b32 v7, v41 offset:272
	ds_write_b32 v7, v42 offset:544
	ds_write_b32 v7, v43 offset:816
	ds_write_b32 v7, v44 offset:4352
	ds_write_b32 v7, v45 offset:4624
	ds_write_b32 v7, v46 offset:4896
	ds_write_b32 v7, v47 offset:5168
	ds_write_b32 v7, v48 offset:8704
	ds_write_b32 v7, v49 offset:8976
	ds_write_b32 v7, v50 offset:9248
	ds_write_b32 v7, v51 offset:9520
	ds_write_b32 v7, v52 offset:13056
	ds_write_b32 v7, v53 offset:13328
	ds_write_b32 v7, v54 offset:13600
	ds_write_b32 v7, v55 offset:13872
	s_waitcnt lgkmcnt(0)
	s_barrier
	ds_read_b128 v[40:43], v8
	ds_read_b128 v[44:47], v8 offset:16
	ds_read_b128 v[48:51], v8 offset:32
	ds_read_b128 v[52:55], v8 offset:48
	s_waitcnt vmcnt(2) lgkmcnt(0)
	v_lshlrev_b32_e32 v11, 16, v56
	v_mul_f32_e32 v40, v40, v11
	v_and_b32_e32 v11, 0xffff0000, v56
	v_mul_f32_e32 v41, v41, v11
	v_lshlrev_b32_e32 v11, 16, v57
	v_mul_f32_e32 v42, v42, v11
	v_and_b32_e32 v11, 0xffff0000, v57
	v_mul_f32_e32 v43, v43, v11
	v_lshlrev_b32_e32 v11, 16, v58
	v_mul_f32_e32 v44, v44, v11
	v_and_b32_e32 v11, 0xffff0000, v58
	v_mul_f32_e32 v45, v45, v11
	v_lshlrev_b32_e32 v11, 16, v59
	v_mul_f32_e32 v46, v46, v11
	v_and_b32_e32 v11, 0xffff0000, v59
	v_mul_f32_e32 v47, v47, v11
	v_lshlrev_b32_e32 v11, 16, v60
	v_mul_f32_e32 v48, v48, v11
	v_and_b32_e32 v11, 0xffff0000, v60
	v_mul_f32_e32 v49, v49, v11
	v_lshlrev_b32_e32 v11, 16, v61
	v_mul_f32_e32 v50, v50, v11
	v_and_b32_e32 v11, 0xffff0000, v61
	v_mul_f32_e32 v51, v51, v11
	v_lshlrev_b32_e32 v11, 16, v62
	v_mul_f32_e32 v52, v52, v11
	v_and_b32_e32 v11, 0xffff0000, v62
	v_mul_f32_e32 v53, v53, v11
	v_lshlrev_b32_e32 v11, 16, v63
	v_mul_f32_e32 v54, v54, v11
	v_and_b32_e32 v11, 0xffff0000, v63
	v_mul_f32_e32 v55, v55, v11
	v_cvt_pk_bf16_f32 v56, v40, v41
	v_cvt_pk_bf16_f32 v57, v42, v43
	v_cvt_pk_bf16_f32 v58, v44, v45
	v_cvt_pk_bf16_f32 v59, v46, v47
	v_cvt_pk_bf16_f32 v60, v48, v49
	v_cvt_pk_bf16_f32 v61, v50, v51
	v_cvt_pk_bf16_f32 v62, v52, v53
	v_cvt_pk_bf16_f32 v63, v54, v55
	s_nop 0
	global_store_dwordx4 v10, v[56:59], s[56:57]
	global_store_dwordx4 v10, v[60:63], s[56:57] offset:16
	s_barrier
